# EPI_Y epilogues (FFN2, attention-output GEMMs): pairs of 8-byte row stores merged into 16-byte stores with v_permlane16_swap (24 dwordx2 -> 12 dwordx4 per tile)
# speedup vs baseline: 1.0448x; 1.0019x over previous
; template <int EPI>
; __device__ __forceinline__ void gemm_tile3(const Params& p, int l, const u16* __restrict__ A, int lda, const u16* __restrict__ Bt, int K, int m0, int n0, unsigned char* smem) {
;     ...
;     __syncthreads();
;     static_assert(EPI == EPI_FFN1 || EPI == EPI_Y, "gemm_tile3 has the plain epilogues only");
;     const int rowb = m0 + wr * 96 + fr;
;     if (EPI == EPI_Y) {
;         u16* dst = (u16*)(p.ws + OFF_Y) + (size_t)rowb * DM + n0 + wc * 64 + fq * 4;
; #pragma unroll
;         for (int i = 0; i < 6; ++i)
; #pragma unroll
;             for (int j = 0; j < 4; ++j) {
;                 u32x2 w; w[0] = pk2(acc[i][j][0], acc[i][j][1]); w[1] = pk2(acc[i][j][2], acc[i][j][3]);
;                 *(u32x2*)(dst + (size_t)(i * 16) * DM + j * 16) = w;
;             }
.LBB0_451:
	v_or_b32_e32 v0, s1, v106
	s_movk_i32 s1, 0x60
	v_mad_u64_u32 v[100:101], s[28:29], v105, s1, v[0:1]
	v_ashrrev_i32_e32 v101, 31, v100
	v_readlane_b32 s16, v249, 16
	v_lshlrev_b64 v[100:101], 11, v[100:101]
	v_readlane_b32 s17, v249, 17
	s_ashr_i32 s1, s0, 31
	v_lshlrev_b32_e32 v0, 7, v99
	v_lshl_add_u64 v[100:101], s[16:17], 0, v[100:101]
	v_lshl_add_u64 v[100:101], s[0:1], 1, v[100:101]
	v_lshl_add_u64 v[98:99], v[100:101], 0, v[0:1]
	v_lshrrev_b32_e32 v0, 1, v104
	v_and_b32_e32 v0, 24, v0
	v_lshl_add_u64 v[98:99], v[98:99], 0, v[0:1]
	v_and_b32_e32 v0, 16, v104
	v_lshrrev_b32_e32 v100, 1, v0
	v_add_u32_e32 v0, v0, v100
	v_lshl_add_u64 v[98:99], v[98:99], 0, v[0:1]
	v_cvt_pk_bf16_f32 v94, v94, v95
	v_cvt_pk_bf16_f32 v95, v96, v97
	v_cvt_pk_bf16_f32 v96, v90, v91
	v_cvt_pk_bf16_f32 v97, v92, v93
	v_cvt_pk_bf16_f32 v86, v86, v87
	v_cvt_pk_bf16_f32 v87, v88, v89
	v_cvt_pk_bf16_f32 v88, v82, v83
	v_cvt_pk_bf16_f32 v89, v84, v85
	v_cvt_pk_bf16_f32 v78, v78, v79
	v_cvt_pk_bf16_f32 v79, v80, v81
	v_cvt_pk_bf16_f32 v80, v74, v75
	v_cvt_pk_bf16_f32 v81, v76, v77
	v_cvt_pk_bf16_f32 v70, v70, v71
	v_cvt_pk_bf16_f32 v71, v72, v73
	v_cvt_pk_bf16_f32 v72, v66, v67
	v_cvt_pk_bf16_f32 v73, v68, v69
	v_cvt_pk_bf16_f32 v62, v62, v63
	v_cvt_pk_bf16_f32 v63, v64, v65
	v_cvt_pk_bf16_f32 v64, v58, v59
	v_cvt_pk_bf16_f32 v65, v60, v61
	v_cvt_pk_bf16_f32 v54, v54, v55
	v_cvt_pk_bf16_f32 v55, v56, v57
	v_cvt_pk_bf16_f32 v56, v50, v51
	v_cvt_pk_bf16_f32 v57, v52, v53
	v_cvt_pk_bf16_f32 v46, v46, v47
	v_cvt_pk_bf16_f32 v47, v48, v49
	v_cvt_pk_bf16_f32 v48, v42, v43
	v_cvt_pk_bf16_f32 v49, v44, v45
	v_cvt_pk_bf16_f32 v38, v38, v39
	v_cvt_pk_bf16_f32 v39, v40, v41
	v_cvt_pk_bf16_f32 v40, v34, v35
	v_cvt_pk_bf16_f32 v41, v36, v37
	v_cvt_pk_bf16_f32 v30, v30, v31
	v_cvt_pk_bf16_f32 v31, v32, v33
	v_cvt_pk_bf16_f32 v32, v26, v27
	v_cvt_pk_bf16_f32 v33, v28, v29
	v_cvt_pk_bf16_f32 v22, v22, v23
	v_cvt_pk_bf16_f32 v23, v24, v25
	v_cvt_pk_bf16_f32 v24, v18, v19
	v_cvt_pk_bf16_f32 v25, v20, v21
	v_cvt_pk_bf16_f32 v14, v14, v15
	v_cvt_pk_bf16_f32 v15, v16, v17
	v_cvt_pk_bf16_f32 v16, v10, v11
	v_cvt_pk_bf16_f32 v17, v12, v13
	v_cvt_pk_bf16_f32 v6, v6, v7
	v_cvt_pk_bf16_f32 v7, v8, v9
	v_cvt_pk_bf16_f32 v8, v2, v3
	v_cvt_pk_bf16_f32 v9, v4, v5
	s_mov_b64 s[28:29], 0x8000
	v_lshl_add_u64 v[90:91], v[98:99], 0, s[28:29]
	s_mov_b64 s[28:29], 0x10000
	v_lshl_add_u64 v[92:93], v[98:99], 0, s[28:29]
	s_mov_b64 s[28:29], 0x18000
	v_lshl_add_u64 v[82:83], v[98:99], 0, s[28:29]
	s_mov_b64 s[28:29], 0x20000
	v_lshl_add_u64 v[84:85], v[98:99], 0, s[28:29]
	s_mov_b64 s[28:29], 0x28000
	v_lshl_add_u64 v[100:101], v[98:99], 0, s[28:29]
	v_permlane16_swap_b32_e32 v94, v96
	v_permlane16_swap_b32_e32 v95, v97
	v_permlane16_swap_b32_e32 v86, v88
	v_permlane16_swap_b32_e32 v87, v89
	v_permlane16_swap_b32_e32 v78, v80
	v_permlane16_swap_b32_e32 v79, v81
	v_permlane16_swap_b32_e32 v70, v72
	v_permlane16_swap_b32_e32 v71, v73
	v_permlane16_swap_b32_e32 v62, v64
	v_permlane16_swap_b32_e32 v63, v65
	v_permlane16_swap_b32_e32 v54, v56
	v_permlane16_swap_b32_e32 v55, v57
	v_permlane16_swap_b32_e32 v46, v48
	v_permlane16_swap_b32_e32 v47, v49
	v_permlane16_swap_b32_e32 v38, v40
	v_permlane16_swap_b32_e32 v39, v41
	v_permlane16_swap_b32_e32 v30, v32
	v_permlane16_swap_b32_e32 v31, v33
	v_permlane16_swap_b32_e32 v22, v24
	v_permlane16_swap_b32_e32 v23, v25
	v_permlane16_swap_b32_e32 v14, v16
	v_permlane16_swap_b32_e32 v15, v17
	v_permlane16_swap_b32_e32 v6, v8
	v_permlane16_swap_b32_e32 v7, v9
	s_add_i32 s50, s50, 1
	s_lshl_b32 s0, s50, 3
	s_or_b32 s0, s0, s53
	s_mul_i32 s0, s0, s52
	s_add_i32 s0, s0, s33
	s_cmp_lt_u32 s0, s38
	s_waitcnt vmcnt(0) lgkmcnt(0)
	s_barrier
	global_store_dwordx4 v[98:99], v[94:97], off
	global_store_dwordx4 v[98:99], v[86:89], off offset:64
	global_store_dwordx4 v[90:91], v[78:81], off
	global_store_dwordx4 v[90:91], v[70:73], off offset:64
	global_store_dwordx4 v[92:93], v[62:65], off
	global_store_dwordx4 v[92:93], v[54:57], off offset:64
	global_store_dwordx4 v[82:83], v[46:49], off
	global_store_dwordx4 v[82:83], v[38:41], off offset:64
	global_store_dwordx4 v[84:85], v[30:33], off
	global_store_dwordx4 v[84:85], v[22:25], off offset:64
	global_store_dwordx4 v[100:101], v[14:17], off
	global_store_dwordx4 v[100:101], v[6:9], off offset:64
	s_cbranch_scc0 .LBB0_464

; template <int EPI>
; __device__ __forceinline__ void gemm_tile3(const Params& p, int l, const u16* __restrict__ A, int lda, const u16* __restrict__ Bt, int K, int m0, int n0, unsigned char* smem) {
;     ...
;     __syncthreads();
;     static_assert(EPI == EPI_FFN1 || EPI == EPI_Y, "gemm_tile3 has the plain epilogues only");
;     const int rowb = m0 + wr * 96 + fr;
;     if (EPI == EPI_Y) {
;         u16* dst = (u16*)(p.ws + OFF_Y) + (size_t)rowb * DM + n0 + wc * 64 + fq * 4;
; #pragma unroll
;         for (int i = 0; i < 6; ++i)
; #pragma unroll
;             for (int j = 0; j < 4; ++j) {
;                 u32x2 w; w[0] = pk2(acc[i][j][0], acc[i][j][1]); w[1] = pk2(acc[i][j][2], acc[i][j][3]);
;                 *(u32x2*)(dst + (size_t)(i * 16) * DM + j * 16) = w;
;             }
.LBB0_770:
	v_or_b32_e32 v0, s1, v106
	s_movk_i32 s1, 0x60
	v_mad_u64_u32 v[100:101], s[28:29], v105, s1, v[0:1]
	v_ashrrev_i32_e32 v101, 31, v100
	v_readlane_b32 s16, v249, 16
	v_lshlrev_b64 v[100:101], 11, v[100:101]
	v_readlane_b32 s17, v249, 17
	s_ashr_i32 s1, s0, 31
	v_lshlrev_b32_e32 v0, 7, v99
	v_lshl_add_u64 v[100:101], s[16:17], 0, v[100:101]
	v_lshl_add_u64 v[100:101], s[0:1], 1, v[100:101]
	v_lshl_add_u64 v[98:99], v[100:101], 0, v[0:1]
	v_lshrrev_b32_e32 v0, 1, v104
	v_and_b32_e32 v0, 24, v0
	v_lshl_add_u64 v[98:99], v[98:99], 0, v[0:1]
	v_and_b32_e32 v0, 16, v104
	v_lshrrev_b32_e32 v100, 1, v0
	v_add_u32_e32 v0, v0, v100
	v_lshl_add_u64 v[98:99], v[98:99], 0, v[0:1]
	v_cvt_pk_bf16_f32 v94, v94, v95
	v_cvt_pk_bf16_f32 v95, v96, v97
	v_cvt_pk_bf16_f32 v96, v90, v91
	v_cvt_pk_bf16_f32 v97, v92, v93
	v_cvt_pk_bf16_f32 v86, v86, v87
	v_cvt_pk_bf16_f32 v87, v88, v89
	v_cvt_pk_bf16_f32 v88, v82, v83
	v_cvt_pk_bf16_f32 v89, v84, v85
	v_cvt_pk_bf16_f32 v78, v78, v79
	v_cvt_pk_bf16_f32 v79, v80, v81
	v_cvt_pk_bf16_f32 v80, v74, v75
	v_cvt_pk_bf16_f32 v81, v76, v77
	v_cvt_pk_bf16_f32 v70, v70, v71
	v_cvt_pk_bf16_f32 v71, v72, v73
	v_cvt_pk_bf16_f32 v72, v66, v67
	v_cvt_pk_bf16_f32 v73, v68, v69
	v_cvt_pk_bf16_f32 v62, v62, v63
	v_cvt_pk_bf16_f32 v63, v64, v65
	v_cvt_pk_bf16_f32 v64, v58, v59
	v_cvt_pk_bf16_f32 v65, v60, v61
	v_cvt_pk_bf16_f32 v54, v54, v55
	v_cvt_pk_bf16_f32 v55, v56, v57
	v_cvt_pk_bf16_f32 v56, v50, v51
	v_cvt_pk_bf16_f32 v57, v52, v53
	v_cvt_pk_bf16_f32 v46, v46, v47
	v_cvt_pk_bf16_f32 v47, v48, v49
	v_cvt_pk_bf16_f32 v48, v42, v43
	v_cvt_pk_bf16_f32 v49, v44, v45
	v_cvt_pk_bf16_f32 v38, v38, v39
	v_cvt_pk_bf16_f32 v39, v40, v41
	v_cvt_pk_bf16_f32 v40, v34, v35
	v_cvt_pk_bf16_f32 v41, v36, v37
	v_cvt_pk_bf16_f32 v30, v30, v31
	v_cvt_pk_bf16_f32 v31, v32, v33
	v_cvt_pk_bf16_f32 v32, v26, v27
	v_cvt_pk_bf16_f32 v33, v28, v29
	v_cvt_pk_bf16_f32 v22, v22, v23
	v_cvt_pk_bf16_f32 v23, v24, v25
	v_cvt_pk_bf16_f32 v24, v18, v19
	v_cvt_pk_bf16_f32 v25, v20, v21
	v_cvt_pk_bf16_f32 v14, v14, v15
	v_cvt_pk_bf16_f32 v15, v16, v17
	v_cvt_pk_bf16_f32 v16, v10, v11
	v_cvt_pk_bf16_f32 v17, v12, v13
	v_cvt_pk_bf16_f32 v6, v6, v7
	v_cvt_pk_bf16_f32 v7, v8, v9
	v_cvt_pk_bf16_f32 v8, v2, v3
	v_cvt_pk_bf16_f32 v9, v4, v5
	s_mov_b64 s[28:29], 0x8000
	v_lshl_add_u64 v[90:91], v[98:99], 0, s[28:29]
	s_mov_b64 s[28:29], 0x10000
	v_lshl_add_u64 v[92:93], v[98:99], 0, s[28:29]
	s_mov_b64 s[28:29], 0x18000
	v_lshl_add_u64 v[82:83], v[98:99], 0, s[28:29]
	s_mov_b64 s[28:29], 0x20000
	v_lshl_add_u64 v[84:85], v[98:99], 0, s[28:29]
	s_mov_b64 s[28:29], 0x28000
	v_lshl_add_u64 v[100:101], v[98:99], 0, s[28:29]
	v_permlane16_swap_b32_e32 v94, v96
	v_permlane16_swap_b32_e32 v95, v97
	v_permlane16_swap_b32_e32 v86, v88
	v_permlane16_swap_b32_e32 v87, v89
	v_permlane16_swap_b32_e32 v78, v80
	v_permlane16_swap_b32_e32 v79, v81
	v_permlane16_swap_b32_e32 v70, v72
	v_permlane16_swap_b32_e32 v71, v73
	v_permlane16_swap_b32_e32 v62, v64
	v_permlane16_swap_b32_e32 v63, v65
	v_permlane16_swap_b32_e32 v54, v56
	v_permlane16_swap_b32_e32 v55, v57
	v_permlane16_swap_b32_e32 v46, v48
	v_permlane16_swap_b32_e32 v47, v49
	v_permlane16_swap_b32_e32 v38, v40
	v_permlane16_swap_b32_e32 v39, v41
	v_permlane16_swap_b32_e32 v30, v32
	v_permlane16_swap_b32_e32 v31, v33
	v_permlane16_swap_b32_e32 v22, v24
	v_permlane16_swap_b32_e32 v23, v25
	v_permlane16_swap_b32_e32 v14, v16
	v_permlane16_swap_b32_e32 v15, v17
	v_permlane16_swap_b32_e32 v6, v8
	v_permlane16_swap_b32_e32 v7, v9
	s_add_i32 s41, s41, 1
	s_lshl_b32 s0, s41, 3
	s_or_b32 s0, s0, s53
	s_mul_i32 s0, s0, s52
	s_add_i32 s0, s0, s33
	s_cmp_ge_u32 s0, s38
	s_waitcnt vmcnt(0) lgkmcnt(0)
	s_barrier
	global_store_dwordx4 v[98:99], v[94:97], off
	global_store_dwordx4 v[98:99], v[86:89], off offset:64
	global_store_dwordx4 v[90:91], v[78:81], off
	global_store_dwordx4 v[90:91], v[70:73], off offset:64
	global_store_dwordx4 v[92:93], v[62:65], off
	global_store_dwordx4 v[92:93], v[54:57], off offset:64
	global_store_dwordx4 v[82:83], v[46:49], off
	global_store_dwordx4 v[82:83], v[38:41], off offset:64
	global_store_dwordx4 v[84:85], v[30:33], off
	global_store_dwordx4 v[84:85], v[22:25], off offset:64
	global_store_dwordx4 v[100:101], v[14:17], off
	global_store_dwordx4 v[100:101], v[6:9], off offset:64
	s_cbranch_scc1 .LBB0_783

; template <int EPI>
; __device__ __forceinline__ void gemm_tile3(const Params& p, int l, const u16* __restrict__ A, int lda, const u16* __restrict__ Bt, int K, int m0, int n0, unsigned char* smem) {
;     ...
;     __syncthreads();
;     static_assert(EPI == EPI_FFN1 || EPI == EPI_Y, "gemm_tile3 has the plain epilogues only");
;     const int rowb = m0 + wr * 96 + fr;
;     if (EPI == EPI_Y) {
;         u16* dst = (u16*)(p.ws + OFF_Y) + (size_t)rowb * DM + n0 + wc * 64 + fq * 4;
; #pragma unroll
;         for (int i = 0; i < 6; ++i)
; #pragma unroll
;             for (int j = 0; j < 4; ++j) {
;                 u32x2 w; w[0] = pk2(acc[i][j][0], acc[i][j][1]); w[1] = pk2(acc[i][j][2], acc[i][j][3]);
;                 *(u32x2*)(dst + (size_t)(i * 16) * DM + j * 16) = w;
;             }
.LBB0_956:
	v_or_b32_e32 v0, s1, v106
	s_movk_i32 s1, 0x60
	v_mad_u64_u32 v[100:101], s[28:29], v105, s1, v[0:1]
	v_ashrrev_i32_e32 v101, 31, v100
	v_readlane_b32 s18, v249, 16
	v_lshlrev_b64 v[100:101], 11, v[100:101]
	v_readlane_b32 s19, v249, 17
	s_ashr_i32 s1, s0, 31
	v_lshlrev_b32_e32 v0, 7, v99
	v_lshl_add_u64 v[100:101], s[18:19], 0, v[100:101]
	v_lshl_add_u64 v[100:101], s[0:1], 1, v[100:101]
	v_lshl_add_u64 v[98:99], v[100:101], 0, v[0:1]
	v_lshrrev_b32_e32 v0, 1, v104
	v_and_b32_e32 v0, 24, v0
	v_lshl_add_u64 v[98:99], v[98:99], 0, v[0:1]
	v_and_b32_e32 v0, 16, v104
	v_lshrrev_b32_e32 v100, 1, v0
	v_add_u32_e32 v0, v0, v100
	v_lshl_add_u64 v[98:99], v[98:99], 0, v[0:1]
	v_cvt_pk_bf16_f32 v94, v94, v95
	v_cvt_pk_bf16_f32 v95, v96, v97
	v_cvt_pk_bf16_f32 v96, v90, v91
	v_cvt_pk_bf16_f32 v97, v92, v93
	v_cvt_pk_bf16_f32 v86, v86, v87
	v_cvt_pk_bf16_f32 v87, v88, v89
	v_cvt_pk_bf16_f32 v88, v82, v83
	v_cvt_pk_bf16_f32 v89, v84, v85
	v_cvt_pk_bf16_f32 v78, v78, v79
	v_cvt_pk_bf16_f32 v79, v80, v81
	v_cvt_pk_bf16_f32 v80, v74, v75
	v_cvt_pk_bf16_f32 v81, v76, v77
	v_cvt_pk_bf16_f32 v70, v70, v71
	v_cvt_pk_bf16_f32 v71, v72, v73
	v_cvt_pk_bf16_f32 v72, v66, v67
	v_cvt_pk_bf16_f32 v73, v68, v69
	v_cvt_pk_bf16_f32 v62, v62, v63
	v_cvt_pk_bf16_f32 v63, v64, v65
	v_cvt_pk_bf16_f32 v64, v58, v59
	v_cvt_pk_bf16_f32 v65, v60, v61
	v_cvt_pk_bf16_f32 v54, v54, v55
	v_cvt_pk_bf16_f32 v55, v56, v57
	v_cvt_pk_bf16_f32 v56, v50, v51
	v_cvt_pk_bf16_f32 v57, v52, v53
	v_cvt_pk_bf16_f32 v46, v46, v47
	v_cvt_pk_bf16_f32 v47, v48, v49
	v_cvt_pk_bf16_f32 v48, v42, v43
	v_cvt_pk_bf16_f32 v49, v44, v45
	v_cvt_pk_bf16_f32 v38, v38, v39
	v_cvt_pk_bf16_f32 v39, v40, v41
	v_cvt_pk_bf16_f32 v40, v34, v35
	v_cvt_pk_bf16_f32 v41, v36, v37
	v_cvt_pk_bf16_f32 v30, v30, v31
	v_cvt_pk_bf16_f32 v31, v32, v33
	v_cvt_pk_bf16_f32 v32, v26, v27
	v_cvt_pk_bf16_f32 v33, v28, v29
	v_cvt_pk_bf16_f32 v22, v22, v23
	v_cvt_pk_bf16_f32 v23, v24, v25
	v_cvt_pk_bf16_f32 v24, v18, v19
	v_cvt_pk_bf16_f32 v25, v20, v21
	v_cvt_pk_bf16_f32 v14, v14, v15
	v_cvt_pk_bf16_f32 v15, v16, v17
	v_cvt_pk_bf16_f32 v16, v10, v11
	v_cvt_pk_bf16_f32 v17, v12, v13
	v_cvt_pk_bf16_f32 v6, v6, v7
	v_cvt_pk_bf16_f32 v7, v8, v9
	v_cvt_pk_bf16_f32 v8, v2, v3
	v_cvt_pk_bf16_f32 v9, v4, v5
	s_mov_b64 s[28:29], 0x8000
	v_lshl_add_u64 v[90:91], v[98:99], 0, s[28:29]
	s_mov_b64 s[28:29], 0x10000
	v_lshl_add_u64 v[92:93], v[98:99], 0, s[28:29]
	s_mov_b64 s[28:29], 0x18000
	v_lshl_add_u64 v[82:83], v[98:99], 0, s[28:29]
	s_mov_b64 s[28:29], 0x20000
	v_lshl_add_u64 v[84:85], v[98:99], 0, s[28:29]
	s_mov_b64 s[28:29], 0x28000
	v_lshl_add_u64 v[100:101], v[98:99], 0, s[28:29]
	v_permlane16_swap_b32_e32 v94, v96
	v_permlane16_swap_b32_e32 v95, v97
	v_permlane16_swap_b32_e32 v86, v88
	v_permlane16_swap_b32_e32 v87, v89
	v_permlane16_swap_b32_e32 v78, v80
	v_permlane16_swap_b32_e32 v79, v81
	v_permlane16_swap_b32_e32 v70, v72
	v_permlane16_swap_b32_e32 v71, v73
	v_permlane16_swap_b32_e32 v62, v64
	v_permlane16_swap_b32_e32 v63, v65
	v_permlane16_swap_b32_e32 v54, v56
	v_permlane16_swap_b32_e32 v55, v57
	v_permlane16_swap_b32_e32 v46, v48
	v_permlane16_swap_b32_e32 v47, v49
	v_permlane16_swap_b32_e32 v38, v40
	v_permlane16_swap_b32_e32 v39, v41
	v_permlane16_swap_b32_e32 v30, v32
	v_permlane16_swap_b32_e32 v31, v33
	v_permlane16_swap_b32_e32 v22, v24
	v_permlane16_swap_b32_e32 v23, v25
	v_permlane16_swap_b32_e32 v14, v16
	v_permlane16_swap_b32_e32 v15, v17
	v_permlane16_swap_b32_e32 v6, v8
	v_permlane16_swap_b32_e32 v7, v9
	s_add_i32 s40, s40, 1
	s_lshl_b32 s0, s40, 3
	s_or_b32 s0, s0, s53
	s_mul_i32 s0, s0, s52
	s_add_i32 s0, s0, s33
	s_cmp_lt_u32 s0, s38
	s_waitcnt vmcnt(0) lgkmcnt(0)
	s_barrier
	global_store_dwordx4 v[98:99], v[94:97], off
	global_store_dwordx4 v[98:99], v[86:89], off offset:64
	global_store_dwordx4 v[90:91], v[78:81], off
	global_store_dwordx4 v[90:91], v[70:73], off offset:64
	global_store_dwordx4 v[92:93], v[62:65], off
	global_store_dwordx4 v[92:93], v[54:57], off offset:64
	global_store_dwordx4 v[82:83], v[46:49], off
	global_store_dwordx4 v[82:83], v[38:41], off offset:64
	global_store_dwordx4 v[84:85], v[30:33], off
	global_store_dwordx4 v[84:85], v[22:25], off offset:64
	global_store_dwordx4 v[100:101], v[14:17], off
	global_store_dwordx4 v[100:101], v[6:9], off offset:64
	s_cbranch_scc0 .LBB0_969
